# speedup vs baseline: 1.0115x; 1.0115x over previous
; __device__ __forceinline__ int otid() { int t; asm volatile("v_mov_b32 %0, %1" : "=v"(t) : "v"((int)threadIdx.x)); return t; }
; #define SETPTR(IT) { const int mt_ = ITEM_MT(IT), nt_ = ITEM_NT(IT); ga = A + (size_t)(mt_ * AROWS + srow) * lda + (skc ^ fs) * 8; gb = Bt + (size_t)(nt_ * 256 + srow) * ldb + (skc ^ fs) * 8; }
; #define ADV() { ga += 32; gb += 32; ck += 32; if (ck == K) { ck = 0; citem += gridDim.x; const int ci_ = citem < total ? citem : total - 1; SETPTR(ci_) } }
; #define WAITSTEP() { if (a2) WAITV(4); else WAITV(3); }
;     ...
;   const int tid = otid(), lane = tid & 63, wid = tid >> 6, wm = wid >> 2, wn = wid & 3, l15 = lane & 15, quad = lane >> 4;
;   const int srow = tid >> 2, skc = tid & 3;
;   constexpr int AROWS = MI * 32, ABYTES = AROWS * 64, STAGE = ABYTES + 16384;
;   constexpr int GRP = 4;
;   const int fr = (-(l15 >> 2)) & 3, fs = (-(srow >> 2)) & 3;
;   const int aoff = (wm * (MI * 16) + l15) * 64 + (quad ^ fr) * 16, boff = ABYTES + (wn * 64 + l15) * 64 + (quad ^ fr) * 16;
;   const int nk = K >> 5;
;   const bool a2 = (MI != 4);
;   const int a2row = (MI == 6 && tid >= 256) ? 64 : 128, a2lds = (MI == 6 && tid >= 256) ? 4096 : 8192;
;   int citem = item, ck = 0;
;   const u16* ga; const u16* gb;
;     ...
;   SETPTR(citem)
;   GLDS(0) ADV()
;   GLDS(STAGE) ADV()
;   WAITSTEP()
;   __builtin_amdgcn_s_barrier();
;   int scur = 0, snext = 2 * STAGE;
.LBB0_1755:
	v_readlane_b32 s2, v255, 10
	v_readlane_b32 s3, v255, 11
	s_andn2_b64 vcc, exec, s[2:3]
	s_cbranch_vccnz .LBB0_1764
	v_mov_b32 v12, v200
	v_readlane_b32 s2, v255, 13
	v_ashrrev_i32_e32 v108, 2, v12
	v_lshrrev_b32_e32 v0, 4, v12
	v_sub_u32_e32 v4, 0, v0
	v_add_u32_e32 v0, s2, v108
	v_ashrrev_i32_e32 v3, 31, v0
	v_mad_u64_u32 v[0:1], s[2:3], v0, s86, 0
	v_mov_b32_e32 v2, v1
	v_mad_u64_u32 v[2:3], s[2:3], v3, s86, v[2:3]
	v_mov_b32_e32 v1, v2
	v_xor_b32_e32 v2, v12, v4
	v_lshlrev_b32_e32 v2, 4, v2
	v_readlane_b32 s2, v255, 14
	v_and_b32_e32 v128, 48, v2
	v_lshl_add_u32 v109, v12, 4, 0
	v_add_u32_e32 v2, s2, v108
	v_ashrrev_i32_e32 v5, 31, v2
	v_mad_u64_u32 v[2:3], s[2:3], v2, s86, 0
	v_mov_b32_e32 v4, v3
	v_mad_u64_u32 v[4:5], s[2:3], v5, s86, v[4:5]
	v_readfirstlane_b32 s2, v109
	v_readfirstlane_b32 s100, v109
	s_mov_b32 m0, s2
	s_movk_i32 s2, 0xff
	v_cmp_lt_i32_e32 vcc, s2, v12
	v_mov_b32_e32 v6, 0x2000
	v_mov_b32_e32 v7, 0x1000
	v_cndmask_b32_e32 v110, v6, v7, vcc
	v_lshl_add_u64 v[0:1], v[0:1], 1, s[6:7]
	v_mov_b32_e32 v3, v4
	v_cndmask_b32_e64 v4, 7, 6, vcc
	v_add_u32_e32 v13, v109, v110
	v_readfirstlane_b32 s101, v110
	v_lshl_add_u64 v[0:1], v[0:1], 0, v[128:129]
	v_lshlrev_b64 v[96:97], v4, s[86:87]
	v_readfirstlane_b32 s2, v13
	v_add_u32_e32 v6, 0x3000, v109
	v_lshl_add_u64 v[2:3], v[2:3], 1, s[4:5]
	global_load_lds_dwordx4 v[0:1], off
	v_lshl_add_u64 v[4:5], v[96:97], 1, v[0:1]
	s_mov_b32 m0, s2
	v_readfirstlane_b32 s2, v6
	v_lshl_add_u64 v[2:3], v[2:3], 0, v[128:129]
	global_load_lds_dwordx4 v[4:5], off
	s_mov_b32 m0, s2
	s_lshl_b64 s[2:3], s[86:87], 8
	v_add_u32_e32 v8, 0x5000, v109
	v_lshl_add_u64 v[6:7], v[2:3], 0, s[2:3]
	v_readfirstlane_b32 s2, v8
	v_add_u32_e32 v14, 0x7000, v109
	global_load_lds_dwordx4 v[2:3], off
	s_mov_b32 m0, s2
	v_readfirstlane_b32 s2, v14
	global_load_lds_dwordx4 v[6:7], off
	v_lshl_add_u64 v[10:11], v[0:1], 0, 64
	s_mov_b32 m0, s2
	v_lshl_add_u64 v[4:5], v[4:5], 0, 64
	global_load_lds_dwordx4 v[10:11], off
	v_add_u32_e32 v10, 0x7000, v13
	v_lshl_add_u64 v[8:9], v[2:3], 0, 64
	v_readfirstlane_b32 s2, v10
	s_mov_b32 m0, s2
	s_mov_b64 s[12:13], 0x80
	global_load_lds_dwordx4 v[4:5], off
	v_add_u32_e32 v4, 0xa000, v109
	v_readlane_b32 s63, v255, 12
	v_readfirstlane_b32 s2, v4
	v_lshl_add_u64 v[4:5], v[6:7], 0, 64
	v_add_u32_e32 v6, 0xc000, v109
	s_mov_b32 m0, s2
	v_readfirstlane_b32 s2, v6
	global_load_lds_dwordx4 v[8:9], off
	s_mov_b32 m0, s2
	s_lshr_b32 s9, s86, 5
	global_load_lds_dwordx4 v[4:5], off
	v_lshrrev_b32_e32 v4, 8, v12
	v_mul_i32_i24_e32 v4, 0x60, v4
	v_and_or_b32 v4, v12, 15, v4
	v_lshlrev_b32_e32 v111, 6, v4
	v_lshlrev_b32_e32 v4, 2, v12
	v_and_b32_e32 v4, 48, v4
	v_sub_u32_e32 v4, 0, v4
	s_waitcnt vmcnt(4)
	v_bitop3_b32 v112, v12, 48, v4 bitop3:0x48
	v_lshlrev_b32_e32 v4, 6, v12
	s_lshl_b64 s[2:3], s[86:87], 7
	s_mov_b32 s62, 0
	v_and_b32_e32 v113, 0x33c0, v4
	v_lshl_add_u64 v[104:105], v[2:3], 0, s[12:13]
	v_lshl_add_u64 v[102:103], v[0:1], 0, s[12:13]
	v_lshl_add_u64 v[98:99], s[6:7], 0, v[128:129]
	v_lshl_add_u64 v[100:101], s[4:5], 0, v[128:129]
	s_mov_b32 s74, 64
	s_mov_b32 s6, 0xe000
	s_mov_b32 s7, s63
	s_barrier
	s_branch .LBB0_1758

; #define MFMA(a, b, c) __builtin_amdgcn_mfma_f32_16x16x32_bf16((a), (b), (c), 0, 0, 0)
; #define ADV() { ga += 32; gb += 32; ck += 32; if (ck == K) { ck = 0; citem += gridDim.x; const int ci_ = citem < total ? citem : total - 1; SETPTR(ci_) } }
; #define WAITSTEP() { if (a2) WAITV(4); else WAITV(3); }
;     ...
;     for (int kt = 0; kt < nk; ++kt) {
;       if (VAR != 1) { const char* base = lds + scur; bf16x8 a[MI], b[4];
; #pragma unroll
;         for (int i = 0; i < 4; ++i) b[i] = *(const bf16x8*)(base + boff + i * 1024);
; #pragma unroll
;         for (int i = 0; i < MI; ++i) a[i] = *(const bf16x8*)(base + aoff + i * 1024);
; #pragma unroll
;         for (int i = 0; i < MI; ++i)
; #pragma unroll
;           for (int j = 0; j < 4; ++j) acc[i][j] = MFMA(a[i], b[j], acc[i][j]);
;         if (VAR != 2) GLDS(snext)
;     ...
;         if (MI == 8) {
;           __builtin_amdgcn_sched_group_barrier(0x100, MI + 4, 0);
; #pragma unroll
;           for (int g = 0; g < 4; ++g) { __builtin_amdgcn_sched_group_barrier(0x008, 7, 0); __builtin_amdgcn_sched_group_barrier(0x010, 1, 0); }
;           __builtin_amdgcn_sched_group_barrier(0x008, 4, 0);
;         } else if (MI == 6) {
;           __builtin_amdgcn_sched_group_barrier(0x100, MI + 4, 0);
; #pragma unroll
;           for (int g = 0; g < 4; ++g) { __builtin_amdgcn_sched_group_barrier(0x008, 5, 0); __builtin_amdgcn_sched_group_barrier(0x010, 1, 0); }
;           __builtin_amdgcn_sched_group_barrier(0x008, 4, 0);
;         }
;     ...
;       }
;       ADV()
;       if (VAR == 2) {} else WAITSTEP()
;       __builtin_amdgcn_s_barrier();
;       scur = (scur == 2 * STAGE) ? 0 : scur + STAGE;
;       snext = (snext == 2 * STAGE) ? 0 : snext + STAGE;
.LBB0_1761:
	s_cmpk_ge_u32 s100, 0x1000
	s_cbranch_scc1 .Lres6_hi
	s_add_i32 s5, s62, 0
	v_add3_u32 v107, s5, v111, v112
	v_add3_u32 v106, s5, v113, v112
	ds_read_b128 v[118:121], v107
	ds_read_b128 v[114:117], v106 offset:12288
	ds_read_b128 v[122:125], v106 offset:13312
	ds_read_b128 v[132:135], v106 offset:14336
	ds_read_b128 v[136:139], v106 offset:15360
	ds_read_b128 v[140:143], v107 offset:1024
	ds_read_b128 v[144:147], v107 offset:2048
	ds_read_b128 v[148:151], v107 offset:3072
	ds_read_b128 v[152:155], v107 offset:4096
	ds_read_b128 v[156:159], v107 offset:5120
	s_add_i32 s5, s6, s100
	s_mov_b32 m0, s5
	v_lshl_add_u64 v[194:195], v[96:97], 1, v[102:103]
	v_lshl_add_u64 v[196:197], s[2:3], 1, v[104:105]
	s_nop 0
	global_load_lds_dwordx4 v[102:103], off
	s_add_i32 m0, s5, s101
	s_nop 0
	global_load_lds_dwordx4 v[194:195], off
	s_add_i32 m0, s5, 0x3000
	s_nop 0
	global_load_lds_dwordx4 v[104:105], off
	s_add_i32 m0, s5, 0x5000
	s_nop 0
	global_load_lds_dwordx4 v[196:197], off
	s_waitcnt lgkmcnt(8)
	v_mfma_f32_16x16x32_bf16 v[92:95], v[118:121], v[114:117], v[92:95]
	s_waitcnt lgkmcnt(7)
	v_mfma_f32_16x16x32_bf16 v[88:91], v[118:121], v[122:125], v[88:91]
	s_waitcnt lgkmcnt(6)
	v_mfma_f32_16x16x32_bf16 v[84:87], v[118:121], v[132:135], v[84:87]
	s_waitcnt lgkmcnt(5)
	v_mfma_f32_16x16x32_bf16 v[80:83], v[118:121], v[136:139], v[80:83]
	s_waitcnt lgkmcnt(4)
	v_mfma_f32_16x16x32_bf16 v[76:79], v[140:143], v[114:117], v[76:79]
	v_mfma_f32_16x16x32_bf16 v[72:75], v[140:143], v[122:125], v[72:75]
	v_mfma_f32_16x16x32_bf16 v[68:71], v[140:143], v[132:135], v[68:71]
	v_mfma_f32_16x16x32_bf16 v[64:67], v[140:143], v[136:139], v[64:67]
	s_waitcnt lgkmcnt(3)
	v_mfma_f32_16x16x32_bf16 v[60:63], v[144:147], v[114:117], v[60:63]
	v_mfma_f32_16x16x32_bf16 v[56:59], v[144:147], v[122:125], v[56:59]
	v_mfma_f32_16x16x32_bf16 v[52:55], v[144:147], v[132:135], v[52:55]
	v_mfma_f32_16x16x32_bf16 v[48:51], v[144:147], v[136:139], v[48:51]
	s_waitcnt lgkmcnt(2)
	v_mfma_f32_16x16x32_bf16 v[36:39], v[148:151], v[114:117], v[36:39]
	v_mfma_f32_16x16x32_bf16 v[32:35], v[148:151], v[122:125], v[32:35]
	v_mfma_f32_16x16x32_bf16 v[40:43], v[148:151], v[132:135], v[40:43]
	v_mfma_f32_16x16x32_bf16 v[44:47], v[148:151], v[136:139], v[44:47]
	s_waitcnt lgkmcnt(1)
	v_mfma_f32_16x16x32_bf16 v[16:19], v[152:155], v[114:117], v[16:19]
	v_mfma_f32_16x16x32_bf16 v[20:23], v[152:155], v[122:125], v[20:23]
	v_mfma_f32_16x16x32_bf16 v[24:27], v[152:155], v[132:135], v[24:27]
	v_mfma_f32_16x16x32_bf16 v[28:31], v[152:155], v[136:139], v[28:31]
	s_waitcnt lgkmcnt(0)
	v_mfma_f32_16x16x32_bf16 v[0:3], v[156:159], v[114:117], v[0:3]
	v_mfma_f32_16x16x32_bf16 v[4:7], v[156:159], v[122:125], v[4:7]
	v_mfma_f32_16x16x32_bf16 v[8:11], v[156:159], v[132:135], v[8:11]
	v_mfma_f32_16x16x32_bf16 v[12:15], v[156:159], v[136:139], v[12:15]
	s_add_i32 s74, s74, 32
	s_cmp_lg_u32 s74, s86
	s_cbranch_scc0 .LBB0_1759
	s_branch .Lres6_adv
.Lres6_hi:
	s_add_i32 s5, s62, 0
	v_add3_u32 v107, s5, v111, v112
	v_add3_u32 v106, s5, v113, v112
	ds_read_b128 v[118:121], v107
	ds_read_b128 v[114:117], v106 offset:12288
	ds_read_b128 v[122:125], v106 offset:13312
	ds_read_b128 v[132:135], v106 offset:14336
	ds_read_b128 v[136:139], v106 offset:15360
	ds_read_b128 v[140:143], v107 offset:1024
	ds_read_b128 v[144:147], v107 offset:2048
	ds_read_b128 v[148:151], v107 offset:3072
	ds_read_b128 v[152:155], v107 offset:4096
	ds_read_b128 v[156:159], v107 offset:5120
	s_waitcnt lgkmcnt(8)
	v_mfma_f32_16x16x32_bf16 v[92:95], v[118:121], v[114:117], v[92:95]
	s_waitcnt lgkmcnt(7)
	v_mfma_f32_16x16x32_bf16 v[88:91], v[118:121], v[122:125], v[88:91]
	s_waitcnt lgkmcnt(6)
	v_mfma_f32_16x16x32_bf16 v[84:87], v[118:121], v[132:135], v[84:87]
	s_waitcnt lgkmcnt(5)
	v_mfma_f32_16x16x32_bf16 v[80:83], v[118:121], v[136:139], v[80:83]
	s_waitcnt lgkmcnt(4)
	v_mfma_f32_16x16x32_bf16 v[76:79], v[140:143], v[114:117], v[76:79]
	v_mfma_f32_16x16x32_bf16 v[72:75], v[140:143], v[122:125], v[72:75]
	v_mfma_f32_16x16x32_bf16 v[68:71], v[140:143], v[132:135], v[68:71]
	v_mfma_f32_16x16x32_bf16 v[64:67], v[140:143], v[136:139], v[64:67]
	s_waitcnt lgkmcnt(3)
	v_mfma_f32_16x16x32_bf16 v[60:63], v[144:147], v[114:117], v[60:63]
	s_add_i32 s5, s6, s100
	s_mov_b32 m0, s5
	v_lshl_add_u64 v[194:195], v[96:97], 1, v[102:103]
	v_lshl_add_u64 v[196:197], s[2:3], 1, v[104:105]
	v_mfma_f32_16x16x32_bf16 v[56:59], v[144:147], v[122:125], v[56:59]
	v_mfma_f32_16x16x32_bf16 v[52:55], v[144:147], v[132:135], v[52:55]
	global_load_lds_dwordx4 v[102:103], off
	s_add_i32 m0, s5, s101
	v_mfma_f32_16x16x32_bf16 v[48:51], v[144:147], v[136:139], v[48:51]
	s_waitcnt lgkmcnt(2)
	v_mfma_f32_16x16x32_bf16 v[36:39], v[148:151], v[114:117], v[36:39]
	v_mfma_f32_16x16x32_bf16 v[32:35], v[148:151], v[122:125], v[32:35]
	v_mfma_f32_16x16x32_bf16 v[40:43], v[148:151], v[132:135], v[40:43]
	global_load_lds_dwordx4 v[194:195], off
	s_add_i32 m0, s5, 0x3000
	v_mfma_f32_16x16x32_bf16 v[44:47], v[148:151], v[136:139], v[44:47]
	s_waitcnt lgkmcnt(1)
	v_mfma_f32_16x16x32_bf16 v[16:19], v[152:155], v[114:117], v[16:19]
	v_mfma_f32_16x16x32_bf16 v[20:23], v[152:155], v[122:125], v[20:23]
	v_mfma_f32_16x16x32_bf16 v[24:27], v[152:155], v[132:135], v[24:27]
	global_load_lds_dwordx4 v[104:105], off
	s_add_i32 m0, s5, 0x5000
	v_mfma_f32_16x16x32_bf16 v[28:31], v[152:155], v[136:139], v[28:31]
	s_waitcnt lgkmcnt(0)
	v_mfma_f32_16x16x32_bf16 v[0:3], v[156:159], v[114:117], v[0:3]
	v_mfma_f32_16x16x32_bf16 v[4:7], v[156:159], v[122:125], v[4:7]
	v_mfma_f32_16x16x32_bf16 v[8:11], v[156:159], v[132:135], v[8:11]
	global_load_lds_dwordx4 v[196:197], off
	v_mfma_f32_16x16x32_bf16 v[12:15], v[156:159], v[136:139], v[12:15]
	s_add_i32 s74, s74, 32
	s_cmp_lg_u32 s74, s86
	s_cbranch_scc0 .LBB0_1759
.Lres6_adv:
	v_lshl_add_u64 v[102:103], v[102:103], 0, 64
	v_lshl_add_u64 v[104:105], v[104:105], 0, 64
	s_branch .LBB0_1760
